# half the blocks (blockIdx bit3) run dil before diff in the attention phase, to mix heavy/light work across the chip
# baseline (speedup 1.0000x reference)
; #define LAS __attribute__((address_space(3)))
; __device__ __forceinline__ void attn_phase(unsigned char* ws, int l, LAS unsigned char* lds, int G) {
;     ...
;     attn_setup(par, l, lds);
;     const LAS float* misc = (const LAS float*)(lds + MISC_OFF);
;     const float lam = misc[16], osc = misc[17];
;     const int wid = __builtin_amdgcn_readfirstlane(threadIdx.x >> 6);
;     const int bx = blockIdx.x;
;     const int vb = (G % 8 == 0) ? (bx % 8) * (G / 8) + bx / 8 : bx;
;     for (int u = vb; u < 768; u += G) {
.LBB0_516:
	s_or_b64 exec, exec, s[12:13]
	s_mov_b32 s92, 0
	s_add_i32 s2, 0, 0x20440
	v_mov_b32_e32 v0, s2
	s_waitcnt lgkmcnt(0)
	s_barrier
	ds_read_b64 v[156:157], v0
	s_and_b32 s2, s74, 7
	s_cmp_eq_u32 s2, 0
	v_readfirstlane_b32 s20, v154
	s_cselect_b64 s[44:45], -1, 0
	s_cmp_lg_u32 s2, 0
	s_mov_b32 s33, s14
	s_cbranch_scc0 .LBB0_518
	s_add_u32 s48, s8, 0xb400000
	s_addc_u32 s49, s9, 0
	s_cmpk_gt_i32 s33, 0x2ff
	s_cbranch_scc0 .LBB0_519
	s_branch .LBB0_551

; __device__ __forceinline__ void attn_phase(unsigned char* ws, int l, LAS unsigned char* lds, int G) {
;     ...
;     for (int u = vb; u < 768; u += G) {
;         const int pair = u >> 6, qb = u & 63;
;         diff_unit(lds, proj, par + P_SUBN + l * 64, pair >> 2, pair & 3, qb, lam, osc);
;     }
;     __syncthreads();
;     for (int bu = vb; bu < 1152; bu += G) {
;         const int sh = bu >> 6, rem = bu & 63, T0 = (rem >> 1) * 512, rho = (rem & 1) * 8 + wid;
;         dil_unit(lds, proj, sh / 6, sh % 6, T0, rho);
;     }
.LBB0_519:
	s_bitcmp1_b32 s14, 3
	s_cbranch_scc0 .Lsw0_diff
	s_mov_b32 s92, 1
	s_mov_b32 s93, s33
	s_mov_b32 s94, s8
	s_mov_b32 s95, s9
	s_branch .LBB0_551

; __device__ __forceinline__ void attn_phase(unsigned char* ws, int l, LAS unsigned char* lds, int G) {
;     ...
;     __syncthreads();
;     for (int bu = vb; bu < 1152; bu += G) {
;         const int sh = bu >> 6, rem = bu & 63, T0 = (rem >> 1) * 512, rho = (rem & 1) * 8 + wid;
;         dil_unit(lds, proj, sh / 6, sh % 6, T0, rho);
.LBB0_551:
	s_cmpk_gt_i32 s33, 0x47f
	s_waitcnt lgkmcnt(0)
	s_barrier
	s_cbranch_scc1 .LBB0_561
	s_cmp_eq_u32 s92, 2
	s_cbranch_scc1 .LBB0_561
	v_lshlrev_b32_e32 v200, 2, v154
	v_add_u32_e32 v200, 0x15c00, v200
	v_add_u32_e32 v201, 0, v154
	v_lshrrev_b32_e32 v204, 4, v201
	v_add_u32_e32 v201, v201, v204
	v_lshlrev_b32_e32 v201, 2, v201
	v_add_u32_e32 v201, 0x8000, v201
	v_add_u32_e32 v202, 512, v154
	v_lshrrev_b32_e32 v204, 4, v202
	v_add_u32_e32 v202, v202, v204
	v_lshlrev_b32_e32 v202, 2, v202
	v_add_u32_e32 v202, 0x8000, v202
	v_add_u32_e32 v203, 1024, v154
	v_lshrrev_b32_e32 v204, 4, v203
	v_add_u32_e32 v203, v203, v204
	v_lshlrev_b32_e32 v203, 2, v203
	v_add_u32_e32 v203, 0x8000, v203
	v_readfirstlane_b32 s82, v154
	s_nop 3
	s_cmp_lt_u32 s82, 128
	s_cbranch_scc0 .Lpt0_two
	ds_read_b32 v205, v200 offset:0
	ds_read_b32 v206, v200 offset:2048
	ds_read_b32 v207, v200 offset:4096
	ds_read_b32 v208, v200 offset:7168
	ds_read_b32 v209, v200 offset:9216
	ds_read_b32 v210, v200 offset:11264
	ds_read_b32 v211, v200 offset:14336
	ds_read_b32 v212, v200 offset:16384
	ds_read_b32 v213, v200 offset:18432
	ds_read_b32 v214, v200 offset:21504
	ds_read_b32 v215, v200 offset:23552
	ds_read_b32 v216, v200 offset:25600
	ds_read_b32 v217, v200 offset:28672
	ds_read_b32 v218, v200 offset:30720
	ds_read_b32 v219, v200 offset:32768
	ds_read_b32 v220, v200 offset:35840
	ds_read_b32 v221, v200 offset:37888
	ds_read_b32 v222, v200 offset:39936
	s_waitcnt lgkmcnt(0)
	ds_write_b32 v201, v205 offset:0
	ds_write_b32 v202, v206 offset:0
	ds_write_b32 v203, v207 offset:0
	ds_write_b32 v201, v208 offset:4896
	ds_write_b32 v202, v209 offset:4896
	ds_write_b32 v203, v210 offset:4896
	ds_write_b32 v201, v211 offset:9792
	ds_write_b32 v202, v212 offset:9792
	ds_write_b32 v203, v213 offset:9792
	ds_write_b32 v201, v214 offset:14688
	ds_write_b32 v202, v215 offset:14688
	ds_write_b32 v203, v216 offset:14688
	ds_write_b32 v201, v217 offset:19584
	ds_write_b32 v202, v218 offset:19584
	ds_write_b32 v203, v219 offset:19584
	ds_write_b32 v201, v220 offset:24480
	ds_write_b32 v202, v221 offset:24480
	ds_write_b32 v203, v222 offset:24480
	s_branch .Lpt0_done

; __device__ __forceinline__ void attn_phase(unsigned char* ws, int l, LAS unsigned char* lds, int G) {
;     ...
;     for (int u = vb; u < 768; u += G) {
;         const int pair = u >> 6, qb = u & 63;
;         diff_unit(lds, proj, par + P_SUBN + l * 64, pair >> 2, pair & 3, qb, lam, osc);
;     }
;     __syncthreads();
;     for (int bu = vb; bu < 1152; bu += G) {
;         const int sh = bu >> 6, rem = bu & 63, T0 = (rem >> 1) * 512, rho = (rem & 1) * 8 + wid;
;         dil_unit(lds, proj, sh / 6, sh % 6, T0, rho);
;     }
.Lsw0_back:
	s_cmp_eq_u32 s92, 1
	s_cbranch_scc0 .LBB0_561
	s_mov_b32 s92, 2
	s_mov_b32 s33, s93
	s_mov_b32 s8, s94
	s_mov_b32 s9, s95
	v_mov_b32_e32 v0, 0x20440
	s_waitcnt lgkmcnt(0)
	s_barrier
	ds_read_b64 v[156:157], v0
	s_branch .Lsw0_diff

; #define LAS __attribute__((address_space(3)))
; __device__ __forceinline__ void attn_phase(unsigned char* ws, int l, LAS unsigned char* lds, int G) {
;     ...
;     attn_setup(par, l, lds);
;     const LAS float* misc = (const LAS float*)(lds + MISC_OFF);
;     const float lam = misc[16], osc = misc[17];
;     const int wid = __builtin_amdgcn_readfirstlane(threadIdx.x >> 6);
;     const int bx = blockIdx.x;
;     const int vb = (G % 8 == 0) ? (bx % 8) * (G / 8) + bx / 8 : bx;
;     for (int u = vb; u < 768; u += G) {
.LBB0_1228:
	s_or_b64 exec, exec, s[12:13]
	s_mov_b32 s92, 0
	s_add_i32 s4, 0, 0x20440
	v_mov_b32_e32 v0, s4
	s_waitcnt lgkmcnt(0)
	s_barrier
	ds_read_b64 v[156:157], v0
	v_readfirstlane_b32 s22, v154
	s_andn2_b64 vcc, exec, s[44:45]
	s_mov_b32 s60, s14
	s_cbranch_vccz .LBB0_1230
	s_add_u32 s44, s40, 0xb400000
	s_addc_u32 s45, s41, 0
	s_cmpk_gt_i32 s60, 0x2ff
	s_cbranch_scc0 .LBB0_1231
	s_branch .LBB0_1263

; __device__ __forceinline__ void attn_phase(unsigned char* ws, int l, LAS unsigned char* lds, int G) {
;     ...
;     for (int u = vb; u < 768; u += G) {
;         const int pair = u >> 6, qb = u & 63;
;         diff_unit(lds, proj, par + P_SUBN + l * 64, pair >> 2, pair & 3, qb, lam, osc);
;     }
;     __syncthreads();
;     for (int bu = vb; bu < 1152; bu += G) {
;         const int sh = bu >> 6, rem = bu & 63, T0 = (rem >> 1) * 512, rho = (rem & 1) * 8 + wid;
;         dil_unit(lds, proj, sh / 6, sh % 6, T0, rho);
;     }
.LBB0_1231:
	s_bitcmp1_b32 s14, 3
	s_cbranch_scc0 .Lsw1_diff
	s_mov_b32 s92, 1
	s_mov_b32 s93, s60
	s_branch .LBB0_1263

; __device__ __forceinline__ void attn_phase(unsigned char* ws, int l, LAS unsigned char* lds, int G) {
;     ...
;     __syncthreads();
;     for (int bu = vb; bu < 1152; bu += G) {
;         const int sh = bu >> 6, rem = bu & 63, T0 = (rem >> 1) * 512, rho = (rem & 1) * 8 + wid;
;         dil_unit(lds, proj, sh / 6, sh % 6, T0, rho);
.LBB0_1263:
	s_cmpk_gt_i32 s60, 0x47f
	s_waitcnt lgkmcnt(0)
	s_barrier
	s_cbranch_scc1 .LBB0_1273
	s_cmp_eq_u32 s92, 2
	s_cbranch_scc1 .LBB0_1273
	v_lshlrev_b32_e32 v200, 2, v154
	v_add_u32_e32 v200, 0x15c00, v200
	v_add_u32_e32 v201, 0, v154
	v_lshrrev_b32_e32 v204, 4, v201
	v_add_u32_e32 v201, v201, v204
	v_lshlrev_b32_e32 v201, 2, v201
	v_add_u32_e32 v201, 0x8000, v201
	v_add_u32_e32 v202, 512, v154
	v_lshrrev_b32_e32 v204, 4, v202
	v_add_u32_e32 v202, v202, v204
	v_lshlrev_b32_e32 v202, 2, v202
	v_add_u32_e32 v202, 0x8000, v202
	v_add_u32_e32 v203, 1024, v154
	v_lshrrev_b32_e32 v204, 4, v203
	v_add_u32_e32 v203, v203, v204
	v_lshlrev_b32_e32 v203, 2, v203
	v_add_u32_e32 v203, 0x8000, v203
	v_readfirstlane_b32 s82, v154
	s_nop 3
	s_cmp_lt_u32 s82, 128
	s_cbranch_scc0 .Lpt1_two
	ds_read_b32 v205, v200 offset:0
	ds_read_b32 v206, v200 offset:2048
	ds_read_b32 v207, v200 offset:4096
	ds_read_b32 v208, v200 offset:7168
	ds_read_b32 v209, v200 offset:9216
	ds_read_b32 v210, v200 offset:11264
	ds_read_b32 v211, v200 offset:14336
	ds_read_b32 v212, v200 offset:16384
	ds_read_b32 v213, v200 offset:18432
	ds_read_b32 v214, v200 offset:21504
	ds_read_b32 v215, v200 offset:23552
	ds_read_b32 v216, v200 offset:25600
	ds_read_b32 v217, v200 offset:28672
	ds_read_b32 v218, v200 offset:30720
	ds_read_b32 v219, v200 offset:32768
	ds_read_b32 v220, v200 offset:35840
	ds_read_b32 v221, v200 offset:37888
	ds_read_b32 v222, v200 offset:39936
	s_waitcnt lgkmcnt(0)
	ds_write_b32 v201, v205 offset:0
	ds_write_b32 v202, v206 offset:0
	ds_write_b32 v203, v207 offset:0
	ds_write_b32 v201, v208 offset:4896
	ds_write_b32 v202, v209 offset:4896
	ds_write_b32 v203, v210 offset:4896
	ds_write_b32 v201, v211 offset:9792
	ds_write_b32 v202, v212 offset:9792
	ds_write_b32 v203, v213 offset:9792
	ds_write_b32 v201, v214 offset:14688
	ds_write_b32 v202, v215 offset:14688
	ds_write_b32 v203, v216 offset:14688
	ds_write_b32 v201, v217 offset:19584
	ds_write_b32 v202, v218 offset:19584
	ds_write_b32 v203, v219 offset:19584
	ds_write_b32 v201, v220 offset:24480
	ds_write_b32 v202, v221 offset:24480
	ds_write_b32 v203, v222 offset:24480
	s_branch .Lpt1_done

; __device__ __forceinline__ void attn_phase(unsigned char* ws, int l, LAS unsigned char* lds, int G) {
;     ...
;     for (int u = vb; u < 768; u += G) {
;         const int pair = u >> 6, qb = u & 63;
;         diff_unit(lds, proj, par + P_SUBN + l * 64, pair >> 2, pair & 3, qb, lam, osc);
;     }
;     __syncthreads();
;     for (int bu = vb; bu < 1152; bu += G) {
;         const int sh = bu >> 6, rem = bu & 63, T0 = (rem >> 1) * 512, rho = (rem & 1) * 8 + wid;
;         dil_unit(lds, proj, sh / 6, sh % 6, T0, rho);
;     }
.Lsw1_back:
	s_cmp_eq_u32 s92, 1
	s_cbranch_scc0 .LBB0_1273
	s_mov_b32 s92, 2
	s_mov_b32 s60, s93
	v_mov_b32_e32 v0, 0x20440
	s_waitcnt lgkmcnt(0)
	s_barrier
	ds_read_b64 v[156:157], v0
	s_branch .Lsw1_diff
